# s_sleep 120 (3us) pacing at the top of each P0 weight-transposer iteration, on top of h1pf
# speedup vs baseline: 1.0126x; 1.0006x over previous
; __device__ __forceinline__ void p0_prologue(const Ptrs& P, LAS unsigned char* lds, int vcu, int G, int tid) {
;     ...
;         for (int it = gw; it < NITEMS; it += NGW) {
;             const int nit = it + NGW; const bool has_n = nit < NITEMS;
;             f32x4 nv[8];
;             const TItem nxt = t_decode(P, has_n ? nit : it, lane); t_load(nxt, nv);
.LBB0_39:
	s_sleep 120
	s_mov_b32 s20, s50
	s_add_i32 s50, s50, s0
	s_cmp_gt_i32 s50, 0xffff
	s_cselect_b64 s[22:23], -1, 0
	s_cmp_lt_i32 s50, 0x10000
	s_cselect_b32 s53, s50, s20
	s_cmpk_gt_i32 s53, 0x3fff
	s_cbranch_scc0 .LBB0_52
	s_add_i32 s20, s53, 0xffffc000
	s_mul_hi_u32 s24, s20, 0xaaaaaaab
	s_lshr_b32 s29, s24, 9
	s_mul_i32 s24, s29, 0x300
	s_sub_i32 s28, s20, s24
	s_lshl_b32 s20, s28, 5
	s_cmpk_gt_u32 s28, 0x1ff
	s_cselect_b64 s[24:25], -1, 0
	s_mov_b64 s[26:27], -1
	s_and_b64 vcc, exec, s[24:25]
	s_cbranch_vccz .LBB0_42
	s_lshl_b32 s26, s28, 10
	s_and_b32 s26, s26, 0x1000
	s_lshl_b32 s27, s28, 4
	s_and_b32 s52, s20, 0x60
	s_and_b32 s27, s27, 0x3f80
	s_or_b32 s26, s52, s26
	s_add_i32 s26, s26, s27
	v_add_u32_e32 v68, s26, v83
	s_mov_b64 s[26:27], 0
